# queue-head snapshot for workgroup classes + grid-barrier acquire invalidate issued before the release-flag poll on the non-leader path
# speedup vs baseline: 1.0156x; 1.0101x over previous
; __device__ __forceinline__ unsigned xb_ld(unsigned* p)              { return __hip_atomic_load(p, __ATOMIC_RELAXED, __HIP_MEMORY_SCOPE_AGENT); }
; __device__ __forceinline__ unsigned xb_add(unsigned* p, unsigned v) { return __hip_atomic_fetch_add(p, v, __ATOMIC_RELAXED, __HIP_MEMORY_SCOPE_AGENT); }
; #define XB_SPIN(cond, bar) do { unsigned _sp = 0; while (cond) { __builtin_amdgcn_s_sleep(1); \
;     if ((++_sp & 255u) == 0u) { if (xb_ld(&(bar)[XB_TMO])) break; if (_sp > XB_SPIN_CAP) { atomicAdd(&(bar)[XB_TMO], 1u); break; } } } } while (0)
; __device__ __forceinline__ void xcd_barrier(const XcdBarrier& b) {
;     asm volatile("s_waitcnt vmcnt(0)" ::: "memory");
;     __syncthreads();
;     if (threadIdx.x == 0) {
;         unsigned* bar = b.bar;
;         __builtin_amdgcn_s_waitcnt(0);
;         unsigned nloc = b.st[0], nx = b.st[1];
;         if (nloc == 0u) { xcd_barrier_complete(bar, b.x, nloc, nx); b.st[0] = nloc; b.st[1] = nx; }
;         const unsigned old = xb_add(&bar[XB_XSUB(b.x)], 1u);
;         const unsigned gen = old / nloc;
;         if (old + 1u == (gen + 1u) * nloc) {
;             __builtin_amdgcn_fence(__ATOMIC_RELEASE, "agent");
;             asm volatile("s_waitcnt vmcnt(0)" ::: "memory");
;             const unsigned og = xb_add(&bar[XB_TOP], 1u);
;             const unsigned tg = og / nx;
;             if (og + 1u == (tg + 1u) * nx) xb_add(&bar[XB_TOPGEN], 1u);
;             else XB_SPIN(xb_ld(&bar[XB_TOPGEN]) == tg, bar);
;             __builtin_amdgcn_fence(__ATOMIC_ACQUIRE, "agent");
;             xb_add(&bar[XB_XGEN(b.x)], 1u);
;             asm volatile("s_waitcnt vmcnt(0)" ::: "memory");
;         } else {
;             XB_SPIN(xb_ld(&bar[XB_XGEN(b.x)]) == gen, bar);
;             __builtin_amdgcn_fence(__ATOMIC_ACQUIRE, "agent");
;             asm volatile("s_waitcnt vmcnt(0)" ::: "memory");
;         }
.LBB0_206:
	s_lshl_b32 s4, s39, 8
	s_add_u32 s27, s33, s4
	s_addc_u32 s26, s38, 0
	v_mov_b32_e32 v1, s27
	v_add_co_u32_e32 v6, vcc, 0x1000, v1
	v_mov_b32_e32 v1, s26
	s_nop 0
	v_addc_co_u32_e32 v7, vcc, 0, v1, vcc
	v_mov_b32_e32 v1, 1
	flat_atomic_add v1, v[6:7], v1 offset:1024 sc0
	v_cvt_f32_u32_e32 v3, v4
	v_sub_u32_e32 v5, 0, v4
	v_rcp_iflag_f32_e32 v3, v3
	s_nop 0
	v_mul_f32_e32 v3, 0x4f7ffffe, v3
	v_cvt_u32_f32_e32 v3, v3
	v_mul_lo_u32 v5, v5, v3
	v_mul_hi_u32 v5, v3, v5
	v_add_u32_e32 v3, v3, v5
	s_waitcnt vmcnt(0) lgkmcnt(0)
	v_mul_hi_u32 v3, v1, v3
	v_mul_lo_u32 v5, v3, v4
	v_add_u32_e32 v6, 1, v1
	v_sub_u32_e32 v1, v1, v5
	v_add_u32_e32 v7, 1, v3
	v_cmp_ge_u32_e32 vcc, v1, v4
	v_sub_u32_e32 v5, v1, v4
	s_nop 0
	v_cndmask_b32_e32 v3, v3, v7, vcc
	v_cndmask_b32_e32 v1, v1, v5, vcc
	v_add_u32_e32 v5, 1, v3
	v_cmp_ge_u32_e32 vcc, v1, v4
	s_nop 1
	v_cndmask_b32_e32 v1, v3, v5, vcc
	v_mad_u64_u32 v[4:5], s[4:5], v4, v1, v[4:5]
	v_cmp_ne_u32_e32 vcc, v6, v4
	s_and_saveexec_b64 s[4:5], vcc
	s_xor_b64 s[4:5], exec, s[4:5]
	s_cbranch_execz .LBB0_219
	buffer_inv sc1
	v_mov_b32_e32 v2, s27
	v_add_co_u32_e32 v2, vcc, 0x2000, v2
	v_mov_b32_e32 v3, s26
	s_nop 0
	v_addc_co_u32_e32 v3, vcc, 0, v3, vcc
	flat_load_dword v2, v[2:3] offset:1024 sc1
	s_add_u32 s10, s27, 0x2400
	s_addc_u32 s11, s26, 0
	s_waitcnt vmcnt(0) lgkmcnt(0)
	v_cmp_eq_u32_e32 vcc, v2, v1
	s_and_saveexec_b64 s[6:7], vcc
	s_cbranch_execz .LBB0_218
	s_add_u32 s8, s2, 0x4200
	s_addc_u32 s9, s3, 0
	s_mov_b32 s28, 1
	s_mov_b64 s[12:13], 0
	s_branch .LBB0_210

; __device__ __forceinline__ unsigned xb_ld(unsigned* p)              { return __hip_atomic_load(p, __ATOMIC_RELAXED, __HIP_MEMORY_SCOPE_AGENT); }
; #define XB_SPIN(cond, bar) do { unsigned _sp = 0; while (cond) { __builtin_amdgcn_s_sleep(1); \
;     if ((++_sp & 255u) == 0u) { if (xb_ld(&(bar)[XB_TMO])) break; if (_sp > XB_SPIN_CAP) { atomicAdd(&(bar)[XB_TMO], 1u); break; } } } } while (0)
; __device__ __forceinline__ void xcd_barrier(const XcdBarrier& b) {
;     ...
;         } else {
;             XB_SPIN(xb_ld(&bar[XB_XGEN(b.x)]) == gen, bar);
;             __builtin_amdgcn_fence(__ATOMIC_ACQUIRE, "agent");
;             asm volatile("s_waitcnt vmcnt(0)" ::: "memory");
;         }
.LBB0_218:
	s_or_b64 exec, exec, s[6:7]
	s_waitcnt vmcnt(0) lgkmcnt(0)
	s_waitcnt vmcnt(0)

; __device__ __forceinline__ unsigned xb_ld(unsigned* p)              { return __hip_atomic_load(p, __ATOMIC_RELAXED, __HIP_MEMORY_SCOPE_AGENT); }
; __device__ __forceinline__ unsigned xb_add(unsigned* p, unsigned v) { return __hip_atomic_fetch_add(p, v, __ATOMIC_RELAXED, __HIP_MEMORY_SCOPE_AGENT); }
; #define XB_SPIN(cond, bar) do { unsigned _sp = 0; while (cond) { __builtin_amdgcn_s_sleep(1); \
;     if ((++_sp & 255u) == 0u) { if (xb_ld(&(bar)[XB_TMO])) break; if (_sp > XB_SPIN_CAP) { atomicAdd(&(bar)[XB_TMO], 1u); break; } } } } while (0)
; __device__ __forceinline__ void xcd_barrier(const XcdBarrier& b) {
;     ...
;     if (threadIdx.x == 0) {
;         unsigned* bar = b.bar;
;         __builtin_amdgcn_s_waitcnt(0);
;         unsigned nloc = b.st[0], nx = b.st[1];
;         if (nloc == 0u) { xcd_barrier_complete(bar, b.x, nloc, nx); b.st[0] = nloc; b.st[1] = nx; }
;         const unsigned old = xb_add(&bar[XB_XSUB(b.x)], 1u);
;         const unsigned gen = old / nloc;
;         if (old + 1u == (gen + 1u) * nloc) {
;             __builtin_amdgcn_fence(__ATOMIC_RELEASE, "agent");
;             asm volatile("s_waitcnt vmcnt(0)" ::: "memory");
;             const unsigned og = xb_add(&bar[XB_TOP], 1u);
;             const unsigned tg = og / nx;
;             if (og + 1u == (tg + 1u) * nx) xb_add(&bar[XB_TOPGEN], 1u);
;             else XB_SPIN(xb_ld(&bar[XB_TOPGEN]) == tg, bar);
;             __builtin_amdgcn_fence(__ATOMIC_ACQUIRE, "agent");
;             xb_add(&bar[XB_XGEN(b.x)], 1u);
;             asm volatile("s_waitcnt vmcnt(0)" ::: "memory");
;         } else {
;             XB_SPIN(xb_ld(&bar[XB_XGEN(b.x)]) == gen, bar);
;             __builtin_amdgcn_fence(__ATOMIC_ACQUIRE, "agent");
;             asm volatile("s_waitcnt vmcnt(0)" ::: "memory");
;         }
.LBB0_270:
	v_readlane_b32 s6, v255, 3
	v_readlane_b32 s7, v255, 4
	v_mov_b32_e32 v1, 1
	s_nop 0
	v_mov_b64_e32 v[6:7], s[6:7]
	flat_atomic_add v5, v[6:7], v1 sc0
	v_cvt_f32_u32_e32 v1, v4
	v_sub_u32_e32 v6, 0, v4
	v_rcp_iflag_f32_e32 v1, v1
	s_nop 0
	v_mul_f32_e32 v1, 0x4f7ffffe, v1
	v_cvt_u32_f32_e32 v1, v1
	v_mul_lo_u32 v6, v6, v1
	v_mul_hi_u32 v6, v1, v6
	v_add_u32_e32 v1, v1, v6
	s_waitcnt vmcnt(0) lgkmcnt(0)
	v_mul_hi_u32 v1, v5, v1
	v_mul_lo_u32 v6, v1, v4
	v_sub_u32_e32 v6, v5, v6
	v_cmp_ge_u32_e32 vcc, v6, v4
	v_add_u32_e32 v7, 1, v1
	s_nop 0
	v_cndmask_b32_e32 v1, v1, v7, vcc
	v_sub_u32_e32 v7, v6, v4
	v_cndmask_b32_e32 v6, v6, v7, vcc
	v_cmp_ge_u32_e32 vcc, v6, v4
	v_add_u32_e32 v6, 1, v1
	s_nop 0
	v_cndmask_b32_e32 v1, v1, v6, vcc
	v_add_u32_e32 v6, 1, v5
	v_mad_u64_u32 v[4:5], s[6:7], v4, v1, v[4:5]
	v_cmp_ne_u32_e32 vcc, v6, v4
	s_and_saveexec_b64 s[6:7], vcc
	s_xor_b64 s[16:17], exec, s[6:7]
	s_cbranch_execz .LBB0_283
	buffer_inv sc1
	v_readlane_b32 s6, v255, 5
	v_readlane_b32 s7, v255, 6
	s_nop 1
	v_mov_b64_e32 v[4:5], s[6:7]
	flat_load_dword v2, v[4:5] sc1
	s_waitcnt vmcnt(0) lgkmcnt(0)
	v_cmp_eq_u32_e32 vcc, v2, v1
	s_and_saveexec_b64 s[20:21], vcc
	s_cbranch_execz .LBB0_282
	s_mov_b32 s5, 1
	s_mov_b64 s[22:23], 0
	s_branch .LBB0_274

; __device__ __forceinline__ unsigned xb_ld(unsigned* p)              { return __hip_atomic_load(p, __ATOMIC_RELAXED, __HIP_MEMORY_SCOPE_AGENT); }
; #define XB_SPIN(cond, bar) do { unsigned _sp = 0; while (cond) { __builtin_amdgcn_s_sleep(1); \
;     if ((++_sp & 255u) == 0u) { if (xb_ld(&(bar)[XB_TMO])) break; if (_sp > XB_SPIN_CAP) { atomicAdd(&(bar)[XB_TMO], 1u); break; } } } } while (0)
; __device__ __forceinline__ void xcd_barrier(const XcdBarrier& b) {
;     ...
;         } else {
;             XB_SPIN(xb_ld(&bar[XB_XGEN(b.x)]) == gen, bar);
;             __builtin_amdgcn_fence(__ATOMIC_ACQUIRE, "agent");
;             asm volatile("s_waitcnt vmcnt(0)" ::: "memory");
;         }
.LBB0_282:
	s_or_b64 exec, exec, s[20:21]
	s_waitcnt vmcnt(0) lgkmcnt(0)
	s_waitcnt vmcnt(0)

; __device__ __forceinline__ unsigned xb_xcc_id() { return (unsigned)__builtin_amdgcn_s_getreg((3 << 11) | 20) & 0xFu; }
; #define WG_DRAW(cls, q) LAS int* slot = (LAS int*)(lds + MISC_OFF + 64); \
;         if (threadIdx.x == 0) *slot = (int)__hip_atomic_fetch_add(XQ_HEAD(cls, q), 1u, RLX_AGENT); \
;         __syncthreads(); const int it = *slot; __syncthreads();
; template <int ATTM> __device__ __forceinline__ void attention_phase(int layer, int lane, int rep, LAS unsigned char* lds, int wave) {
;     ...
;     if ((ATTM & 2) && PK(2)) {
; #pragma unroll 1
;         for (int qq = 0; qq < 8; ++qq) { const int q = ((int)(xb_xcc_id() & 7u) + qq) & 7;
;             for (;;) { WG_DRAW(0, q); if (it >= 32) break;
.LBB0_548:
	s_cmp_lg_u32 s6, 0
	s_cbranch_scc1 .Lmy_qs_dif_inc
	v_cmp_gt_u32_e32 vcc, 8, v0
	s_and_saveexec_b64 s[14:15], vcc
	s_cbranch_execz .Lmy_qs_dif_b
	s_lshl_b32 s4, s33, 7
	s_add_i32 s4, s4, 0x20000

; __device__ __forceinline__ unsigned xb_xcc_id() { return (unsigned)__builtin_amdgcn_s_getreg((3 << 11) | 20) & 0xFu; }
; #define WG_DRAW(cls, q) LAS int* slot = (LAS int*)(lds + MISC_OFF + 64); \
;         if (threadIdx.x == 0) *slot = (int)__hip_atomic_fetch_add(XQ_HEAD(cls, q), 1u, RLX_AGENT); \
;         __syncthreads(); const int it = *slot; __syncthreads();
; template <int ATTM> __device__ __forceinline__ void attention_phase(int layer, int lane, int rep, LAS unsigned char* lds, int wave) {
;     ...
;     if ((ATTM & 2) && PK(2)) {
; #pragma unroll 1
;         for (int qq = 0; qq < 8; ++qq) { const int q = ((int)(xb_xcc_id() & 7u) + qq) & 7;
;             for (;;) { WG_DRAW(0, q); if (it >= 32) break;
	s_load_dwordx2 s[12:13], s[0:1], 0x98
	v_lshl_add_u32 v5, v0, 7, s4
	s_waitcnt lgkmcnt(0)
	global_load_dword v6, v5, s[12:13] sc1
	s_waitcnt vmcnt(0)
	v_cmp_le_u32_e32 vcc, 0x20, v6
	s_nop 1
	s_and_b32 s4, vcc_lo, 0xff
	v_mov_b32_e32 v6, s4
	v_mov_b32_e32 v5, s87
	ds_write_b32 v5, v6 offset:4

; __device__ __forceinline__ unsigned xb_xcc_id() { return (unsigned)__builtin_amdgcn_s_getreg((3 << 11) | 20) & 0xFu; }
; #define WG_DRAW(cls, q) LAS int* slot = (LAS int*)(lds + MISC_OFF + 64); \
;         if (threadIdx.x == 0) *slot = (int)__hip_atomic_fetch_add(XQ_HEAD(cls, q), 1u, RLX_AGENT); \
;         __syncthreads(); const int it = *slot; __syncthreads();
; template <int ATTM> __device__ __forceinline__ void attention_phase(int layer, int lane, int rep, LAS unsigned char* lds, int wave) {
;     ...
;         for (int qq = 0; qq < 8; ++qq) { const int q = ((int)(xb_xcc_id() & 7u) + qq) & 7; const int two = q + 8 < BATCH * 7 ? 1 : 0;
;             for (;;) { WG_DRAW(1, q); if (it >= (two ? 32 : 16)) break;
.LBB0_614:
	s_cmp_lg_u32 s7, 0
	s_cbranch_scc1 .Lmy_qs_fox_inc
	v_cmp_gt_u32_e32 vcc, 8, v0
	s_and_saveexec_b64 s[14:15], vcc
	s_cbranch_execz .Lmy_qs_fox_b
	s_lshl_b32 s4, s6, 7
	s_add_i32 s4, s4, 0x20000

; __device__ __forceinline__ unsigned xb_xcc_id() { return (unsigned)__builtin_amdgcn_s_getreg((3 << 11) | 20) & 0xFu; }
; #define WG_DRAW(cls, q) LAS int* slot = (LAS int*)(lds + MISC_OFF + 64); \
;         if (threadIdx.x == 0) *slot = (int)__hip_atomic_fetch_add(XQ_HEAD(cls, q), 1u, RLX_AGENT); \
;         __syncthreads(); const int it = *slot; __syncthreads();
; template <int ATTM> __device__ __forceinline__ void attention_phase(int layer, int lane, int rep, LAS unsigned char* lds, int wave) {
;     ...
;         for (int qq = 0; qq < 8; ++qq) { const int q = ((int)(xb_xcc_id() & 7u) + qq) & 7; const int two = q + 8 < BATCH * 7 ? 1 : 0;
;             for (;;) { WG_DRAW(1, q); if (it >= (two ? 32 : 16)) break;
	s_load_dwordx2 s[12:13], s[0:1], 0x98
	v_lshl_add_u32 v5, v0, 7, s4
	v_mov_b32_e32 v7, 32
	v_cmp_gt_u32_e32 vcc, 6, v0
	s_nop 1
	v_cndmask_b32_e32 v7, 16, v7, vcc
	s_waitcnt lgkmcnt(0)
	global_load_dword v6, v5, s[12:13] sc1
	s_waitcnt vmcnt(0)
	v_cmp_le_u32_e32 vcc, v7, v6
	s_nop 1
	s_and_b32 s4, vcc_lo, 0xff
	v_mov_b32_e32 v6, s4
	v_mov_b32_e32 v5, s87
	ds_write_b32 v5, v6 offset:4

; __device__ __forceinline__ unsigned xb_xcc_id() { return (unsigned)__builtin_amdgcn_s_getreg((3 << 11) | 20) & 0xFu; }
; #define ARG_WS() ((unsigned char*)karg64(8 * 19))
; #define WG_DRAW(cls, q) LAS int* slot = (LAS int*)(lds + MISC_OFF + 64); \
;         if (threadIdx.x == 0) *slot = (int)__hip_atomic_fetch_add(XQ_HEAD(cls, q), 1u, RLX_AGENT); \
;         __syncthreads(); const int it = *slot; __syncthreads();
; template <int ATTM> __device__ __forceinline__ void attention_phase(int layer, int lane, int rep, LAS unsigned char* lds, int wave) {
;     ...
;         for (int qq = 0; qq < 8; ++qq) { const int q = ((int)(xb_xcc_id() & 7u) + qq) & 7;
;             for (;;) { WG_DRAW(2, q); if (it >= 32) break; unsigned char* ws = ARG_WS();
.LBB0_669:
	s_cmp_lg_u32 s59, 0
	s_cbranch_scc1 .Lmy_qs_nsa_inc
	v_cmp_gt_u32_e32 vcc, 8, v0
	s_and_saveexec_b64 s[14:15], vcc
	s_cbranch_execz .Lmy_qs_nsa_b
	v_readlane_b32 s4, v255, 26
	s_lshl_b32 s4, s4, 7
	s_add_i32 s4, s4, 0x20000

; __device__ __forceinline__ unsigned xb_xcc_id() { return (unsigned)__builtin_amdgcn_s_getreg((3 << 11) | 20) & 0xFu; }
; #define ARG_WS() ((unsigned char*)karg64(8 * 19))
; #define WG_DRAW(cls, q) LAS int* slot = (LAS int*)(lds + MISC_OFF + 64); \
;         if (threadIdx.x == 0) *slot = (int)__hip_atomic_fetch_add(XQ_HEAD(cls, q), 1u, RLX_AGENT); \
;         __syncthreads(); const int it = *slot; __syncthreads();
; template <int ATTM> __device__ __forceinline__ void attention_phase(int layer, int lane, int rep, LAS unsigned char* lds, int wave) {
;     ...
;         for (int qq = 0; qq < 8; ++qq) { const int q = ((int)(xb_xcc_id() & 7u) + qq) & 7;
;             for (;;) { WG_DRAW(2, q); if (it >= 32) break; unsigned char* ws = ARG_WS();
	s_load_dwordx2 s[12:13], s[0:1], 0x98
	v_lshl_add_u32 v5, v0, 7, s4
	s_waitcnt lgkmcnt(0)
	global_load_dword v6, v5, s[12:13] sc1
	s_waitcnt vmcnt(0)
	v_cmp_le_u32_e32 vcc, 0x20, v6
	s_nop 1
	s_and_b32 s4, vcc_lo, 0xff
	v_mov_b32_e32 v6, s4
	v_mov_b32_e32 v5, s87
	ds_write_b32 v5, v6 offset:4

; __device__ __forceinline__ unsigned xb_ld(unsigned* p)              { return __hip_atomic_load(p, __ATOMIC_RELAXED, __HIP_MEMORY_SCOPE_AGENT); }
; __device__ __forceinline__ unsigned xb_add(unsigned* p, unsigned v) { return __hip_atomic_fetch_add(p, v, __ATOMIC_RELAXED, __HIP_MEMORY_SCOPE_AGENT); }
; #define XB_SPIN(cond, bar) do { unsigned _sp = 0; while (cond) { __builtin_amdgcn_s_sleep(1); \
;     if ((++_sp & 255u) == 0u) { if (xb_ld(&(bar)[XB_TMO])) break; if (_sp > XB_SPIN_CAP) { atomicAdd(&(bar)[XB_TMO], 1u); break; } } } } while (0)
; __device__ __forceinline__ void xcd_barrier(const XcdBarrier& b) {
;     ...
;     if (threadIdx.x == 0) {
;         unsigned* bar = b.bar;
;         __builtin_amdgcn_s_waitcnt(0);
;         unsigned nloc = b.st[0], nx = b.st[1];
;         if (nloc == 0u) { xcd_barrier_complete(bar, b.x, nloc, nx); b.st[0] = nloc; b.st[1] = nx; }
;         const unsigned old = xb_add(&bar[XB_XSUB(b.x)], 1u);
;         const unsigned gen = old / nloc;
;         if (old + 1u == (gen + 1u) * nloc) {
;             __builtin_amdgcn_fence(__ATOMIC_RELEASE, "agent");
;             asm volatile("s_waitcnt vmcnt(0)" ::: "memory");
;             const unsigned og = xb_add(&bar[XB_TOP], 1u);
;             const unsigned tg = og / nx;
;             if (og + 1u == (tg + 1u) * nx) xb_add(&bar[XB_TOPGEN], 1u);
;             else XB_SPIN(xb_ld(&bar[XB_TOPGEN]) == tg, bar);
;             __builtin_amdgcn_fence(__ATOMIC_ACQUIRE, "agent");
;             xb_add(&bar[XB_XGEN(b.x)], 1u);
;             asm volatile("s_waitcnt vmcnt(0)" ::: "memory");
;         } else {
;             XB_SPIN(xb_ld(&bar[XB_XGEN(b.x)]) == gen, bar);
;             __builtin_amdgcn_fence(__ATOMIC_ACQUIRE, "agent");
;             asm volatile("s_waitcnt vmcnt(0)" ::: "memory");
;         }
.LBB0_1996:
	v_readlane_b32 s6, v255, 3
	v_readlane_b32 s7, v255, 4
	v_mov_b32_e32 v1, 1
	s_nop 0
	v_mov_b64_e32 v[6:7], s[6:7]
	flat_atomic_add v5, v[6:7], v1 sc0
	v_cvt_f32_u32_e32 v1, v4
	v_sub_u32_e32 v6, 0, v4
	v_rcp_iflag_f32_e32 v1, v1
	s_nop 0
	v_mul_f32_e32 v1, 0x4f7ffffe, v1
	v_cvt_u32_f32_e32 v1, v1
	v_mul_lo_u32 v6, v6, v1
	v_mul_hi_u32 v6, v1, v6
	v_add_u32_e32 v1, v1, v6
	s_waitcnt vmcnt(0) lgkmcnt(0)
	v_mul_hi_u32 v1, v5, v1
	v_mul_lo_u32 v6, v1, v4
	v_sub_u32_e32 v6, v5, v6
	v_cmp_ge_u32_e32 vcc, v6, v4
	v_add_u32_e32 v7, 1, v1
	s_nop 0
	v_cndmask_b32_e32 v1, v1, v7, vcc
	v_sub_u32_e32 v7, v6, v4
	v_cndmask_b32_e32 v6, v6, v7, vcc
	v_cmp_ge_u32_e32 vcc, v6, v4
	v_add_u32_e32 v6, 1, v1
	s_nop 0
	v_cndmask_b32_e32 v1, v1, v6, vcc
	v_add_u32_e32 v6, 1, v5
	v_mad_u64_u32 v[4:5], s[6:7], v4, v1, v[4:5]
	v_cmp_ne_u32_e32 vcc, v6, v4
	s_and_saveexec_b64 s[6:7], vcc
	s_xor_b64 s[14:15], exec, s[6:7]
	s_cbranch_execz .LBB0_2009
	buffer_inv sc1
	v_readlane_b32 s6, v255, 5
	v_readlane_b32 s7, v255, 6
	s_nop 1
	v_mov_b64_e32 v[4:5], s[6:7]
	flat_load_dword v2, v[4:5] sc1
	s_waitcnt vmcnt(0) lgkmcnt(0)
	v_cmp_eq_u32_e32 vcc, v2, v1
	s_and_saveexec_b64 s[16:17], vcc
	s_cbranch_execz .LBB0_2008
	s_mov_b32 s5, 1
	s_mov_b64 s[20:21], 0
	s_branch .LBB0_2000

; __device__ __forceinline__ unsigned xb_ld(unsigned* p)              { return __hip_atomic_load(p, __ATOMIC_RELAXED, __HIP_MEMORY_SCOPE_AGENT); }
; #define XB_SPIN(cond, bar) do { unsigned _sp = 0; while (cond) { __builtin_amdgcn_s_sleep(1); \
;     if ((++_sp & 255u) == 0u) { if (xb_ld(&(bar)[XB_TMO])) break; if (_sp > XB_SPIN_CAP) { atomicAdd(&(bar)[XB_TMO], 1u); break; } } } } while (0)
; __device__ __forceinline__ void xcd_barrier(const XcdBarrier& b) {
;     ...
;         } else {
;             XB_SPIN(xb_ld(&bar[XB_XGEN(b.x)]) == gen, bar);
;             __builtin_amdgcn_fence(__ATOMIC_ACQUIRE, "agent");
;             asm volatile("s_waitcnt vmcnt(0)" ::: "memory");
;         }
.LBB0_2008:
	s_or_b64 exec, exec, s[16:17]
	s_waitcnt vmcnt(0) lgkmcnt(0)
	s_waitcnt vmcnt(0)

; __device__ __forceinline__ unsigned xb_ld(unsigned* p)              { return __hip_atomic_load(p, __ATOMIC_RELAXED, __HIP_MEMORY_SCOPE_AGENT); }
; __device__ __forceinline__ unsigned xb_add(unsigned* p, unsigned v) { return __hip_atomic_fetch_add(p, v, __ATOMIC_RELAXED, __HIP_MEMORY_SCOPE_AGENT); }
; #define XB_SPIN(cond, bar) do { unsigned _sp = 0; while (cond) { __builtin_amdgcn_s_sleep(1); \
;     if ((++_sp & 255u) == 0u) { if (xb_ld(&(bar)[XB_TMO])) break; if (_sp > XB_SPIN_CAP) { atomicAdd(&(bar)[XB_TMO], 1u); break; } } } } while (0)
; __device__ __forceinline__ void xcd_barrier(const XcdBarrier& b) {
;     ...
;     if (threadIdx.x == 0) {
;         unsigned* bar = b.bar;
;         __builtin_amdgcn_s_waitcnt(0);
;         unsigned nloc = b.st[0], nx = b.st[1];
;         if (nloc == 0u) { xcd_barrier_complete(bar, b.x, nloc, nx); b.st[0] = nloc; b.st[1] = nx; }
;         const unsigned old = xb_add(&bar[XB_XSUB(b.x)], 1u);
;         const unsigned gen = old / nloc;
;         if (old + 1u == (gen + 1u) * nloc) {
;             __builtin_amdgcn_fence(__ATOMIC_RELEASE, "agent");
;             asm volatile("s_waitcnt vmcnt(0)" ::: "memory");
;             const unsigned og = xb_add(&bar[XB_TOP], 1u);
;             const unsigned tg = og / nx;
;             if (og + 1u == (tg + 1u) * nx) xb_add(&bar[XB_TOPGEN], 1u);
;             else XB_SPIN(xb_ld(&bar[XB_TOPGEN]) == tg, bar);
;             __builtin_amdgcn_fence(__ATOMIC_ACQUIRE, "agent");
;             xb_add(&bar[XB_XGEN(b.x)], 1u);
;             asm volatile("s_waitcnt vmcnt(0)" ::: "memory");
;         } else {
;             XB_SPIN(xb_ld(&bar[XB_XGEN(b.x)]) == gen, bar);
;             __builtin_amdgcn_fence(__ATOMIC_ACQUIRE, "agent");
;             asm volatile("s_waitcnt vmcnt(0)" ::: "memory");
;         }
.LBB0_2259:
	v_readlane_b32 s4, v255, 3
	v_readlane_b32 s5, v255, 4
	v_mov_b32_e32 v1, 1
	s_nop 0
	v_mov_b64_e32 v[6:7], s[4:5]
	flat_atomic_add v5, v[6:7], v1 sc0
	v_cvt_f32_u32_e32 v1, v4
	v_sub_u32_e32 v6, 0, v4
	v_rcp_iflag_f32_e32 v1, v1
	s_nop 0
	v_mul_f32_e32 v1, 0x4f7ffffe, v1
	v_cvt_u32_f32_e32 v1, v1
	v_mul_lo_u32 v6, v6, v1
	v_mul_hi_u32 v6, v1, v6
	v_add_u32_e32 v1, v1, v6
	s_waitcnt vmcnt(0) lgkmcnt(0)
	v_mul_hi_u32 v1, v5, v1
	v_mul_lo_u32 v6, v1, v4
	v_sub_u32_e32 v6, v5, v6
	v_cmp_ge_u32_e32 vcc, v6, v4
	v_add_u32_e32 v7, 1, v1
	s_nop 0
	v_cndmask_b32_e32 v1, v1, v7, vcc
	v_sub_u32_e32 v7, v6, v4
	v_cndmask_b32_e32 v6, v6, v7, vcc
	v_cmp_ge_u32_e32 vcc, v6, v4
	v_add_u32_e32 v6, 1, v1
	s_nop 0
	v_cndmask_b32_e32 v1, v1, v6, vcc
	v_add_u32_e32 v6, 1, v5
	v_mad_u64_u32 v[4:5], s[4:5], v4, v1, v[4:5]
	v_cmp_ne_u32_e32 vcc, v6, v4
	s_and_saveexec_b64 s[4:5], vcc
	s_xor_b64 s[14:15], exec, s[4:5]
	s_cbranch_execz .LBB0_2272
	buffer_inv sc1
	v_readlane_b32 s4, v255, 5
	v_readlane_b32 s5, v255, 6
	s_nop 1
	v_mov_b64_e32 v[4:5], s[4:5]
	flat_load_dword v2, v[4:5] sc1
	s_waitcnt vmcnt(0) lgkmcnt(0)
	v_cmp_eq_u32_e32 vcc, v2, v1
	s_and_saveexec_b64 s[16:17], vcc
	s_cbranch_execz .LBB0_2271
	s_mov_b32 s4, 1
	s_mov_b64 s[20:21], 0
	s_branch .LBB0_2263
